# residual-tile init: unpack deferred until after the K-loop prologue's second DMA batch is issued (residual loads overlap the prologue round trips)
# baseline (speedup 1.0000x reference)
.LBB0_5:
	s_or_b64 exec, exec, s[6:7]
	s_cmp_ge_i32 s82, s83
	s_cbranch_scc1 .LBB0_1060
	s_cmpk_gt_i32 s83, 0x3e8
	s_cselect_b64 s[6:7], -1, 0
	v_writelane_b32 v253, s6, 4
	v_lshrrev_b32_e32 v1, 20, v0
	v_lshrrev_b32_e32 v0, 10, v0
	v_writelane_b32 v253, s7, 5
	s_add_u32 s6, s0, 0xc0200
	s_addc_u32 s7, s1, 0
	s_add_u32 s18, s0, 0xc0400
	s_addc_u32 s19, s1, 0
	s_add_u32 s20, s0, 0xc0500
	s_addc_u32 s21, s1, 0
	s_add_u32 s22, s0, 0xc0600
	s_addc_u32 s23, s1, 0
	s_add_u32 s24, s0, 0xc0700
	v_writelane_b32 v253, s6, 6
	s_addc_u32 s25, s1, 0
	v_or_b32_e32 v0, v0, v1
	v_writelane_b32 v253, s7, 7
	s_add_u32 s6, s0, 0xc0800
	s_addc_u32 s7, s1, 0
	v_writelane_b32 v253, s6, 8
	v_mov_b32_e32 v1, 0
	v_mbcnt_lo_u32_b32 v2, -1, 0
	v_writelane_b32 v253, s7, 9
	s_add_u32 s6, s0, 0xc0900
	s_addc_u32 s7, s1, 0
	v_writelane_b32 v253, s6, 10
	v_mov_b32_e32 v171, 0x3727c5ac
	v_mov_b32_e32 v172, 0x260
	v_writelane_b32 v253, s7, 11
	s_add_u32 s6, s0, 0xc0a00
	s_addc_u32 s7, s1, 0
	v_writelane_b32 v253, s6, 12
	v_mov_b32_e32 v173, 1
	v_mbcnt_hi_u32_b32 v174, -1, v2
	v_writelane_b32 v253, s7, 13
	s_add_u32 s6, s0, 0xc0b00
	s_addc_u32 s7, s1, 0
	v_writelane_b32 v253, s6, 14
	v_mov_b32_e32 v175, 0xff800000
	v_mov_b32_e32 v176, 0x78
	v_writelane_b32 v253, s7, 15
	s_add_u32 s6, s0, 0xc0c00
	s_addc_u32 s7, s1, 0
	v_writelane_b32 v253, s6, 16
	v_mov_b64_e32 v[140:141], 0x60
	v_mov_b32_e32 v177, 0x1080
	v_writelane_b32 v253, s7, 17
	s_add_u32 s6, s0, 0xc0d00
	s_addc_u32 s7, s1, 0
	v_writelane_b32 v253, s6, 18
	v_mov_b32_e32 v178, 0x480
	v_mov_b32_e32 v179, 0x840000
	v_writelane_b32 v253, s7, 19
	s_add_u32 s6, s0, 0xc0e00
	s_addc_u32 s7, s1, 0
	v_writelane_b32 v253, s6, 20
	v_mov_b32_e32 v252, 0x1450
	v_mov_b32_e32 v184, 0x2490
	v_writelane_b32 v253, s7, 21
	s_add_u32 s6, s0, 0xc0f00
	s_addc_u32 s7, s1, 0
	v_writelane_b32 v253, s6, 22
	v_mov_b32_e32 v185, 0x28a0
	v_mov_b32_e32 v196, v1
	v_writelane_b32 v253, s7, 23
	s_add_u32 s6, s0, 0xc1000
	s_addc_u32 s7, s1, 0
	v_writelane_b32 v253, s6, 24
	v_mov_b32_e32 v197, v1
	v_mov_b32_e32 v186, 0x4f70000
	v_writelane_b32 v253, s7, 25
	s_add_u32 s6, s0, 0xc1100
	s_addc_u32 s7, s1, 0
	v_writelane_b32 v253, s6, 26
	v_mov_b32_e32 v187, 0x4b70000
	s_movk_i32 s33, 0x1080
	v_writelane_b32 v253, s7, 27
	s_add_u32 s6, s0, 0xc1200
	s_addc_u32 s7, s1, 0
	v_writelane_b32 v253, s6, 28
	s_mov_b32 s51, 0xf800000
	s_mov_b32 s63, 0
	v_writelane_b32 v253, s7, 29
	s_add_u32 s6, s0, 0xc1300
	s_addc_u32 s7, s1, 0
	v_writelane_b32 v253, s6, 30
	s_cmp_eq_u32 s2, 15
	s_mov_b64 s[68:69], 0x2400
	v_writelane_b32 v253, s7, 31
	s_cselect_b64 s[6:7], -1, 0
	v_writelane_b32 v253, s6, 32
	s_cmp_eq_u32 s2, 14
	s_mov_b64 s[56:57], 0x80
	v_writelane_b32 v253, s7, 33
	s_cselect_b64 s[6:7], -1, 0
	v_writelane_b32 v253, s6, 34
	s_cmp_eq_u32 s2, 13
	s_mov_b64 s[42:43], 0x100
	v_writelane_b32 v253, s7, 35
	s_cselect_b64 s[6:7], -1, 0
	v_writelane_b32 v253, s6, 36
	s_cmp_eq_u32 s2, 12
	s_mov_b64 s[46:47], 0x10000
	v_writelane_b32 v253, s7, 37
	s_cselect_b64 s[6:7], -1, 0
	v_writelane_b32 v253, s6, 38
	s_cmp_eq_u32 s2, 11
	s_nop 0
	v_writelane_b32 v253, s7, 39
	s_cselect_b64 s[6:7], -1, 0
	v_writelane_b32 v253, s6, 40
	s_cmp_eq_u32 s2, 10
	s_nop 0
	v_writelane_b32 v253, s7, 41
	s_cselect_b64 s[6:7], -1, 0
	v_writelane_b32 v253, s6, 42
	s_cmp_eq_u32 s2, 9
	s_nop 0
	v_writelane_b32 v253, s7, 43
	s_cselect_b64 s[6:7], -1, 0
	v_writelane_b32 v253, s6, 44
	s_cmp_eq_u32 s2, 8
	s_nop 0
	v_writelane_b32 v253, s7, 45
	s_cselect_b64 s[6:7], -1, 0
	v_writelane_b32 v253, s6, 46
	s_cmp_eq_u32 s2, 7
	s_nop 0
	v_writelane_b32 v253, s7, 47
	s_cselect_b64 s[6:7], -1, 0
	v_writelane_b32 v253, s6, 48
	s_cmp_eq_u32 s2, 6
	s_nop 0
	v_writelane_b32 v253, s7, 49
	s_cselect_b64 s[6:7], -1, 0
	v_writelane_b32 v253, s6, 50
	s_cmp_eq_u32 s2, 5
	s_nop 0
	v_writelane_b32 v253, s7, 51
	s_cselect_b64 s[6:7], -1, 0
	v_writelane_b32 v253, s6, 52
	s_cmp_eq_u32 s2, 4
	s_nop 0
	v_writelane_b32 v253, s7, 53
	s_cselect_b64 s[6:7], -1, 0
	v_writelane_b32 v253, s6, 54
	s_cmp_eq_u32 s2, 3
	s_nop 0
	v_writelane_b32 v253, s7, 55
	s_cselect_b64 s[6:7], -1, 0
	v_writelane_b32 v253, s6, 56
	s_cmp_eq_u32 s2, 2
	s_nop 0
	v_writelane_b32 v253, s7, 57
	s_cselect_b64 s[6:7], -1, 0
	v_writelane_b32 v253, s6, 58
	s_cmp_eq_u32 s2, 1
	s_nop 0
	v_writelane_b32 v253, s7, 59
	s_cselect_b64 s[6:7], -1, 0
	v_writelane_b32 v253, s6, 60
	s_cmp_eq_u32 s2, 0
	s_nop 0
	v_writelane_b32 v253, s7, 61
	s_cselect_b64 s[6:7], -1, 0
	s_lshl_b32 s2, s2, 8
	s_add_u32 s2, s4, s2
	s_addc_u32 s3, s5, 0
	s_add_u32 s4, s2, 0x1400
	s_addc_u32 s5, s3, 0
	v_writelane_b32 v254, s4, 0
	s_add_u32 s2, s2, 0x2400
	s_addc_u32 s3, s3, 0
	v_writelane_b32 v254, s5, 1
	v_writelane_b32 v254, s2, 2
	v_writelane_b32 v253, s6, 62
	s_nop 0
	v_writelane_b32 v254, s3, 3
	s_add_u32 s2, s0, 0xc3400
	s_addc_u32 s3, s1, 0
	v_writelane_b32 v254, s2, 4
	s_add_u32 s0, s0, 0xc3500
	s_addc_u32 s1, s1, 0
	v_writelane_b32 v254, s3, 5
	v_writelane_b32 v254, s0, 6
	v_writelane_b32 v253, s7, 63
	s_movk_i32 s3, 0x1000
	v_writelane_b32 v254, s1, 7
	s_load_dword s1, s[78:79], 0xb8
	s_movk_i32 s0, 0x3ff
	v_and_or_b32 v0, v0, s0, v170
	s_mul_i32 s0, s81, s80
	s_waitcnt lgkmcnt(0)
	s_mul_i32 s0, s0, s1
	v_writelane_b32 v254, s0, 8
	s_add_i32 s0, 0, 0x20ff0
	v_writelane_b32 v254, s0, 9
	s_add_i32 s0, 0, 0x20ff4
	v_writelane_b32 v254, s0, 10
	v_cmp_eq_u32_e64 s[0:1], 0, v0
	s_nop 1
	v_writelane_b32 v254, s0, 11
	s_nop 1
	v_writelane_b32 v254, s1, 12
	v_writelane_b32 v254, s76, 13
	v_writelane_b32 v254, s78, 14
	s_mov_b32 s0, s80
	s_nop 0
	v_writelane_b32 v254, s79, 15
	v_writelane_b32 v254, s0, 16
	s_nop 1
	v_writelane_b32 v254, s1, 17
	v_writelane_b32 v254, s18, 18
	s_nop 1
	v_writelane_b32 v254, s19, 19
	v_writelane_b32 v254, s20, 20
	s_nop 1
	v_writelane_b32 v254, s21, 21
	v_writelane_b32 v254, s22, 22
	s_nop 1
	v_writelane_b32 v254, s23, 23
	v_writelane_b32 v254, s24, 24
	s_nop 1
	v_writelane_b32 v254, s25, 25
	s_mov_b32 s0, 0
	v_writelane_b32 v255, s0, 59
	s_branch .LBB0_10

.LBB0_184:
	s_lshl_b32 s11, s5, 6
	v_lshlrev_b32_e32 v155, 3, v153
	s_andn2_b64 vcc, exec, s[0:1]
	s_lshl_b32 s10, s4, 5
	s_cbranch_vccnz .LBB0_187
	s_lshl_b32 s0, s50, 8
	s_add_i32 s0, s0, s11
	v_or_b32_e32 v0, s0, v154
	s_lshl_b32 s0, s2, 8
	s_or_b32 s0, s0, s10
	v_or_b32_e32 v2, s0, v155
	s_waitcnt vmcnt(0)
	v_cndmask_b32_e64 v4, 0, 1, s[38:39]
	v_ashrrev_i32_e32 v3, 31, v2
	v_cmp_ne_u32_e64 s[0:1], 1, v4
	s_andn2_b64 vcc, exec, s[38:39]
	s_mov_b64 s[6:7], -1
	s_cbranch_vccnz .LBB0_188
	v_mul_u32_u24_e32 v134, 0x1080, v0
	v_lshl_add_u32 v134, v2, 1, v134
	global_load_dwordx4 v[8:11], v134, s[14:15]
	global_load_dwordx4 v[16:19], v134, s[14:15] offset:256
	v_add_u32_e32 v135, 0x10800, v134
	global_load_dwordx4 v[24:27], v135, s[14:15]
	global_load_dwordx4 v[32:35], v135, s[14:15] offset:256
	v_add_u32_e32 v135, 0x21000, v134
	global_load_dwordx4 v[40:43], v135, s[14:15]
	global_load_dwordx4 v[48:51], v135, s[14:15] offset:256
	v_add_u32_e32 v135, 0x31800, v134
	global_load_dwordx4 v[56:59], v135, s[14:15]
	global_load_dwordx4 v[64:67], v135, s[14:15] offset:256
	v_add_u32_e32 v135, 0x84000, v134
	global_load_dwordx4 v[72:75], v135, s[14:15]
	global_load_dwordx4 v[80:83], v135, s[14:15] offset:256
	v_add_u32_e32 v135, 0x94800, v134
	global_load_dwordx4 v[88:91], v135, s[14:15]
	global_load_dwordx4 v[96:99], v135, s[14:15] offset:256
	v_add_u32_e32 v135, 0xa5000, v134
	global_load_dwordx4 v[104:107], v135, s[14:15]
	global_load_dwordx4 v[112:115], v135, s[14:15] offset:256
	v_add_u32_e32 v135, 0xb5800, v134
	global_load_dwordx4 v[120:123], v135, s[14:15]
	global_load_dwordx4 v[128:131], v135, s[14:15] offset:256
	s_mov_b32 s6, 1
	v_writelane_b32 v255, s6, 59
	s_branch .LBB0_218

.LBB0_220:
	s_add_i32 m0, s90, 0x18000
	v_lshl_add_u64 v[2:3], v[2:3], 0, s[56:57]
	s_waitcnt vmcnt(2)
	s_barrier
	global_load_lds_dwordx4 v[2:3], off
	v_lshl_add_u64 v[2:3], v[132:133], 0, s[56:57]
	s_add_i32 m0, s90, 0x1a000
	s_add_i32 s94, s90, 0x8000
	global_load_lds_dwordx4 v[2:3], off
	v_lshl_add_u64 v[2:3], v[138:139], 0, s[56:57]
	s_mov_b32 m0, s94
	s_add_i32 s95, s90, 0xa000
	global_load_lds_dwordx4 v[2:3], off
	v_lshl_add_u64 v[2:3], v[150:151], 0, s[56:57]
	s_mov_b32 m0, s95
	v_or_b32_e32 v151, s11, v154
	global_load_lds_dwordx4 v[2:3], off
	s_add_i32 m0, s90, 0x1c000
	v_lshl_add_u64 v[2:3], v[134:135], 0, s[56:57]
	global_load_lds_dwordx4 v[2:3], off
	v_lshl_add_u64 v[2:3], v[136:137], 0, s[56:57]
	s_add_i32 m0, s90, 0x1e000
	v_lshlrev_b32_e32 v0, 6, v151
	global_load_lds_dwordx4 v[2:3], off
	v_lshlrev_b32_e32 v2, 4, v153
	s_movk_i32 s0, 0x3c0
	v_lshlrev_b32_e32 v3, 2, v151
	s_lshr_b32 s96, s81, 6
	v_and_or_b32 v0, v0, s0, v2
	s_lshl_b32 s0, s5, 13
	v_and_b32_e32 v3, 32, v3
	v_bitop3_b32 v3, v0, s0, v3 bitop3:0xde
	v_lshl_or_b32 v0, v154, 6, v2
	s_lshl_b32 s0, s4, 12
	v_lshlrev_b32_e32 v2, 2, v154
	s_add_i32 s97, s96, -2
	v_and_b32_e32 v2, 32, v2
	s_cmpk_lt_u32 s9, 0x100
	v_bitop3_b32 v188, v0, s0, v2 bitop3:0xde
	s_cselect_b64 s[64:65], -1, 0
	s_lshl_b32 s0, s5, 4
	s_lshl_b32 s1, s4, 2
	s_or_b32 s0, s1, s0
	s_add_i32 s1, 0, 0x20000
	s_ashr_i32 s86, s87, 31
	s_lshr_b32 s40, s8, 6
	s_add_u32 s41, s18, 0x1ff00000
	s_addc_u32 s44, s19, 0
	s_add_u32 s4, s18, 0x15300000
	v_mov_b32_e32 v0, 0xfffe0000
	s_addc_u32 s5, s19, 0
	s_abs_i32 s45, s88
	v_and_or_b32 v189, v152, 7, v0
	v_cvt_f32_u32_e32 v0, s45
	v_or_b32_e32 v2, s0, v153
	v_lshl_or_b32 v190, v2, 4, v154
	v_writelane_b32 v254, s81, 37
	v_rcp_iflag_f32_e32 v2, v0
	v_writelane_b32 v254, s4, 39
	s_movk_i32 s0, 0x100
	v_lshl_add_u32 v191, v190, 2, s1
	v_mul_f32_e32 v2, 0x4f7ffffe, v2
	v_cvt_u32_f32_e32 v2, v2
	v_writelane_b32 v254, s5, 40
	v_cmp_gt_i32_e64 s[4:5], s0, v190
	s_sub_i32 s0, 0, s45
	v_readfirstlane_b32 s1, v2
	s_mul_i32 s0, s0, s1
	v_or_b32_e32 v150, s10, v155
	s_mul_hi_u32 s0, s1, s0
	v_lshlrev_b32_e32 v0, 2, v150
	s_ashr_i32 s52, s88, 31
	s_add_i32 s8, s1, s0
	v_cmp_eq_u32_e64 s[6:7], 0, v153
	v_lshl_add_u64 v[152:153], s[16:17], 0, v[0:1]
	s_add_u32 s0, s54, 0x80
	v_add_u32_e32 v0, v158, v156
	s_addc_u32 s1, s55, 0
	v_add_lshl_u32 v0, v0, v157, 1
	v_readlane_b32 vcc_lo, v255, 59
	s_cmp_eq_u32 vcc_lo, 0
	s_cbranch_scc1 .Lri_skip
	v_lshlrev_b32_e32 v4, 16, v8
	v_and_b32_e32 v5, 0xffff0000, v8
	v_lshlrev_b32_e32 v6, 16, v9
	v_and_b32_e32 v7, 0xffff0000, v9
	v_lshlrev_b32_e32 v8, 16, v10
	v_and_b32_e32 v9, 0xffff0000, v10
	v_lshlrev_b32_e32 v10, 16, v11
	v_and_b32_e32 v11, 0xffff0000, v11
	v_lshlrev_b32_e32 v12, 16, v16
	v_and_b32_e32 v13, 0xffff0000, v16
	v_lshlrev_b32_e32 v14, 16, v17
	v_and_b32_e32 v15, 0xffff0000, v17
	v_lshlrev_b32_e32 v16, 16, v18
	v_and_b32_e32 v17, 0xffff0000, v18
	v_lshlrev_b32_e32 v18, 16, v19
	v_and_b32_e32 v19, 0xffff0000, v19
	v_lshlrev_b32_e32 v20, 16, v24
	v_and_b32_e32 v21, 0xffff0000, v24
	v_lshlrev_b32_e32 v22, 16, v25
	v_and_b32_e32 v23, 0xffff0000, v25
	v_lshlrev_b32_e32 v24, 16, v26
	v_and_b32_e32 v25, 0xffff0000, v26
	v_lshlrev_b32_e32 v26, 16, v27
	v_and_b32_e32 v27, 0xffff0000, v27
	v_lshlrev_b32_e32 v28, 16, v32
	v_and_b32_e32 v29, 0xffff0000, v32
	v_lshlrev_b32_e32 v30, 16, v33
	v_and_b32_e32 v31, 0xffff0000, v33
	v_lshlrev_b32_e32 v32, 16, v34
	v_and_b32_e32 v33, 0xffff0000, v34
	v_lshlrev_b32_e32 v34, 16, v35
	v_and_b32_e32 v35, 0xffff0000, v35
	v_lshlrev_b32_e32 v36, 16, v40
	v_and_b32_e32 v37, 0xffff0000, v40
	v_lshlrev_b32_e32 v38, 16, v41
	v_and_b32_e32 v39, 0xffff0000, v41
	v_lshlrev_b32_e32 v40, 16, v42
	v_and_b32_e32 v41, 0xffff0000, v42
	v_lshlrev_b32_e32 v42, 16, v43
	v_and_b32_e32 v43, 0xffff0000, v43
	v_lshlrev_b32_e32 v44, 16, v48
	v_and_b32_e32 v45, 0xffff0000, v48
	v_lshlrev_b32_e32 v46, 16, v49
	v_and_b32_e32 v47, 0xffff0000, v49
	v_lshlrev_b32_e32 v48, 16, v50
	v_and_b32_e32 v49, 0xffff0000, v50
	v_lshlrev_b32_e32 v50, 16, v51
	v_and_b32_e32 v51, 0xffff0000, v51
	v_lshlrev_b32_e32 v52, 16, v56
	v_and_b32_e32 v53, 0xffff0000, v56
	v_lshlrev_b32_e32 v54, 16, v57
	v_and_b32_e32 v55, 0xffff0000, v57
	v_lshlrev_b32_e32 v56, 16, v58
	v_and_b32_e32 v57, 0xffff0000, v58
	v_lshlrev_b32_e32 v58, 16, v59
	v_and_b32_e32 v59, 0xffff0000, v59
	v_lshlrev_b32_e32 v60, 16, v64
	v_and_b32_e32 v61, 0xffff0000, v64
	v_lshlrev_b32_e32 v62, 16, v65
	v_and_b32_e32 v63, 0xffff0000, v65
	v_lshlrev_b32_e32 v64, 16, v66
	v_and_b32_e32 v65, 0xffff0000, v66
	v_lshlrev_b32_e32 v66, 16, v67
	v_and_b32_e32 v67, 0xffff0000, v67
	v_lshlrev_b32_e32 v68, 16, v72
	v_and_b32_e32 v69, 0xffff0000, v72
	v_lshlrev_b32_e32 v70, 16, v73
	v_and_b32_e32 v71, 0xffff0000, v73
	v_lshlrev_b32_e32 v72, 16, v74
	v_and_b32_e32 v73, 0xffff0000, v74
	v_lshlrev_b32_e32 v74, 16, v75
	v_and_b32_e32 v75, 0xffff0000, v75
	v_lshlrev_b32_e32 v76, 16, v80
	v_and_b32_e32 v77, 0xffff0000, v80
	v_lshlrev_b32_e32 v78, 16, v81
	v_and_b32_e32 v79, 0xffff0000, v81
	v_lshlrev_b32_e32 v80, 16, v82
	v_and_b32_e32 v81, 0xffff0000, v82
	v_lshlrev_b32_e32 v82, 16, v83
	v_and_b32_e32 v83, 0xffff0000, v83
	v_lshlrev_b32_e32 v84, 16, v88
	v_and_b32_e32 v85, 0xffff0000, v88
	v_lshlrev_b32_e32 v86, 16, v89
	v_and_b32_e32 v87, 0xffff0000, v89
	v_lshlrev_b32_e32 v88, 16, v90
	v_and_b32_e32 v89, 0xffff0000, v90
	v_lshlrev_b32_e32 v90, 16, v91
	v_and_b32_e32 v91, 0xffff0000, v91
	v_lshlrev_b32_e32 v92, 16, v96
	v_and_b32_e32 v93, 0xffff0000, v96
	v_lshlrev_b32_e32 v94, 16, v97
	v_and_b32_e32 v95, 0xffff0000, v97
	v_lshlrev_b32_e32 v96, 16, v98
	v_and_b32_e32 v97, 0xffff0000, v98
	v_lshlrev_b32_e32 v98, 16, v99
	v_and_b32_e32 v99, 0xffff0000, v99
	v_lshlrev_b32_e32 v100, 16, v104
	v_and_b32_e32 v101, 0xffff0000, v104
	v_lshlrev_b32_e32 v102, 16, v105
	v_and_b32_e32 v103, 0xffff0000, v105
	v_lshlrev_b32_e32 v104, 16, v106
	v_and_b32_e32 v105, 0xffff0000, v106
	v_lshlrev_b32_e32 v106, 16, v107
	v_and_b32_e32 v107, 0xffff0000, v107
	v_lshlrev_b32_e32 v108, 16, v112
	v_and_b32_e32 v109, 0xffff0000, v112
	v_lshlrev_b32_e32 v110, 16, v113
	v_and_b32_e32 v111, 0xffff0000, v113
	v_lshlrev_b32_e32 v112, 16, v114
	v_and_b32_e32 v113, 0xffff0000, v114
	v_lshlrev_b32_e32 v114, 16, v115
	v_and_b32_e32 v115, 0xffff0000, v115
	v_lshlrev_b32_e32 v116, 16, v120
	v_and_b32_e32 v117, 0xffff0000, v120
	v_lshlrev_b32_e32 v118, 16, v121
	v_and_b32_e32 v119, 0xffff0000, v121
	v_lshlrev_b32_e32 v120, 16, v122
	v_and_b32_e32 v121, 0xffff0000, v122
	v_lshlrev_b32_e32 v122, 16, v123
	v_and_b32_e32 v123, 0xffff0000, v123
	v_lshlrev_b32_e32 v124, 16, v128
	v_and_b32_e32 v125, 0xffff0000, v128
	v_lshlrev_b32_e32 v126, 16, v129
	v_and_b32_e32 v127, 0xffff0000, v129
	v_lshlrev_b32_e32 v128, 16, v130
	v_and_b32_e32 v129, 0xffff0000, v130
	v_lshlrev_b32_e32 v130, 16, v131
	v_and_b32_e32 v131, 0xffff0000, v131
	s_mov_b32 vcc_lo, 0
	s_nop 0
	v_writelane_b32 v255, vcc_lo, 59
.Lri_skip:
	s_waitcnt vmcnt(6)
	v_lshl_add_u64 v[154:155], s[0:1], 0, v[0:1]
	v_add_u32_e32 v0, v161, v159
	v_writelane_b32 v254, s4, 41
	v_add_lshl_u32 v0, v0, v160, 1
	s_mov_b32 s67, 0
	v_writelane_b32 v254, s5, 42
	s_mov_b32 s37, s63
	v_lshl_add_u64 v[156:157], s[0:1], 0, v[0:1]
	v_add_u32_e32 v192, 0, v3
	s_barrier
	s_branch .LBB0_223
